# stack12 + grid barrier: first-arriving workgroup of each XCD issues an early buffer_wbl2 so the last arriver's mandatory write-back finds the L2 mostly clean
# baseline (speedup 1.0000x reference)
; __device__ __forceinline__ unsigned xb_ld(unsigned* p)              { return __hip_atomic_load(p, __ATOMIC_RELAXED, __HIP_MEMORY_SCOPE_AGENT); }
; __device__ __forceinline__ unsigned xb_add(unsigned* p, unsigned v) { return __hip_atomic_fetch_add(p, v, __ATOMIC_RELAXED, __HIP_MEMORY_SCOPE_AGENT); }
; #define XB_SPIN(cond, bar) do { unsigned _sp = 0; while (cond) { __builtin_amdgcn_s_sleep(1); \
;     if ((++_sp & 255u) == 0u) { if (xb_ld(&(bar)[XB_TMO])) break; if (_sp > XB_SPIN_CAP) { atomicAdd(&(bar)[XB_TMO], 1u); break; } } } } while (0)
; __device__ __forceinline__ void xcd_barrier(const XcdBarrier& b) {
;     ...
;         const unsigned old = xb_add(&bar[XB_XSUB(bx)], 1u);
;         const unsigned gen = old / nloc;
;         if (old + 1u == (gen + 1u) * nloc) {
;             __builtin_amdgcn_fence(__ATOMIC_RELEASE, "agent");
;             asm volatile("s_waitcnt vmcnt(0)" ::: "memory");
;             const unsigned og = xb_add(&bar[XB_TOP], 1u);
;             const unsigned tg = og / nx;
;             if (og + 1u == (tg + 1u) * nx) xb_add(&bar[XB_TOPGEN], 1u);
;             else XB_SPIN(xb_ld(&bar[XB_TOPGEN]) == tg, bar);
;             __builtin_amdgcn_fence(__ATOMIC_ACQUIRE, "agent");
;             asm volatile("s_waitcnt vmcnt(0)" ::: "memory");
;         } else {
;             XB_SPIN(xb_ld(&bar[XB_TOPGEN]) == gen, bar);
.LBB0_225:
	s_lshl_b32 s1, s1, 6
	s_add_i32 s92, s1, 0x500
	s_lshl_b64 s[6:7], s[92:93], 2
	s_add_u32 s6, s52, s6
	s_addc_u32 s7, s53, s7
	v_mov_b64_e32 v[4:5], s[6:7]
	v_mov_b32_e32 v3, 1
	flat_atomic_add v4, v[4:5], v3 sc0
	v_cvt_f32_u32_e32 v3, v2
	v_sub_u32_e32 v5, 0, v2
	v_rcp_iflag_f32_e32 v3, v3
	s_nop 0
	v_mul_f32_e32 v3, 0x4f7ffffe, v3
	v_cvt_u32_f32_e32 v3, v3
	v_mul_lo_u32 v5, v5, v3
	v_mul_hi_u32 v5, v3, v5
	v_add_u32_e32 v3, v3, v5
	s_waitcnt vmcnt(0) lgkmcnt(0)
	v_mul_hi_u32 v3, v4, v3
	v_mul_lo_u32 v5, v3, v2
	v_sub_u32_e32 v5, v4, v5
	v_cmp_ge_u32_e32 vcc, v5, v2
	v_add_u32_e32 v6, 1, v3
	s_nop 0
	v_cndmask_b32_e32 v3, v3, v6, vcc
	v_sub_u32_e32 v6, v5, v2
	v_cndmask_b32_e32 v5, v5, v6, vcc
	v_cmp_ge_u32_e32 vcc, v5, v2
	v_add_u32_e32 v5, 1, v3
	v_add_u32_e32 v6, 1, v4
	v_cndmask_b32_e32 v3, v3, v5, vcc
	v_mad_u64_u32 v[4:5], s[6:7], v2, v3, v[2:3]
	v_cmp_ne_u32_e32 vcc, v6, v4
	s_and_saveexec_b64 s[6:7], vcc
	s_xor_b64 s[6:7], exec, s[6:7]
	s_cbranch_execz .LBB0_238
	v_sub_u32_e32 v0, v4, v2
	v_add_u32_e32 v0, 1, v0
	v_cmp_eq_u32_e32 vcc, v6, v0
	s_cbranch_vccz .Lno_early_wb_0
	buffer_wbl2 sc1
.Lno_early_wb_0:
	v_mov_b32_e32 v0, s52
	v_add_co_u32_e32 v4, vcc, 0x3000, v0
	v_mov_b32_e32 v0, s53
	s_nop 0
	v_addc_co_u32_e32 v5, vcc, 0, v0, vcc
	flat_load_dword v0, v[4:5] offset:1280 sc1
	s_add_u32 s10, s52, 0x3500
	s_addc_u32 s11, s53, 0
	s_waitcnt vmcnt(0) lgkmcnt(0)
	v_cmp_eq_u32_e32 vcc, v0, v3
	s_and_saveexec_b64 s[8:9], vcc
	s_cbranch_execz .LBB0_237
	s_mov_b32 s1, 1
	s_mov_b64 s[12:13], 0
	s_branch .LBB0_229

; __device__ __forceinline__ unsigned xb_ld(unsigned* p)              { return __hip_atomic_load(p, __ATOMIC_RELAXED, __HIP_MEMORY_SCOPE_AGENT); }
; __device__ __forceinline__ unsigned xb_add(unsigned* p, unsigned v) { return __hip_atomic_fetch_add(p, v, __ATOMIC_RELAXED, __HIP_MEMORY_SCOPE_AGENT); }
; #define XB_SPIN(cond, bar) do { unsigned _sp = 0; while (cond) { __builtin_amdgcn_s_sleep(1); \
;     if ((++_sp & 255u) == 0u) { if (xb_ld(&(bar)[XB_TMO])) break; if (_sp > XB_SPIN_CAP) { atomicAdd(&(bar)[XB_TMO], 1u); break; } } } } while (0)
; __device__ __forceinline__ void xcd_barrier(const XcdBarrier& b) {
;     ...
;         const unsigned old = xb_add(&bar[XB_XSUB(bx)], 1u);
;         const unsigned gen = old / nloc;
;         if (old + 1u == (gen + 1u) * nloc) {
;             __builtin_amdgcn_fence(__ATOMIC_RELEASE, "agent");
;             asm volatile("s_waitcnt vmcnt(0)" ::: "memory");
;             const unsigned og = xb_add(&bar[XB_TOP], 1u);
;             const unsigned tg = og / nx;
;             if (og + 1u == (tg + 1u) * nx) xb_add(&bar[XB_TOPGEN], 1u);
;             else XB_SPIN(xb_ld(&bar[XB_TOPGEN]) == tg, bar);
;             __builtin_amdgcn_fence(__ATOMIC_ACQUIRE, "agent");
;             asm volatile("s_waitcnt vmcnt(0)" ::: "memory");
;         } else {
;             XB_SPIN(xb_ld(&bar[XB_TOPGEN]) == gen, bar);
.LBB0_1050:
	s_lshl_b32 s1, s1, 6
	s_add_i32 s92, s1, 0x500
	s_lshl_b64 s[8:9], s[92:93], 2
	s_add_u32 s8, s64, s8
	s_addc_u32 s9, s65, s9
	v_mov_b64_e32 v[4:5], s[8:9]
	v_mov_b32_e32 v3, 1
	flat_atomic_add v4, v[4:5], v3 sc0
	v_cvt_f32_u32_e32 v3, v2
	v_sub_u32_e32 v5, 0, v2
	v_rcp_iflag_f32_e32 v3, v3
	s_nop 0
	v_mul_f32_e32 v3, 0x4f7ffffe, v3
	v_cvt_u32_f32_e32 v3, v3
	v_mul_lo_u32 v5, v5, v3
	v_mul_hi_u32 v5, v3, v5
	v_add_u32_e32 v3, v3, v5
	s_waitcnt vmcnt(0) lgkmcnt(0)
	v_mul_hi_u32 v3, v4, v3
	v_mul_lo_u32 v5, v3, v2
	v_sub_u32_e32 v5, v4, v5
	v_cmp_ge_u32_e32 vcc, v5, v2
	v_add_u32_e32 v6, 1, v3
	s_nop 0
	v_cndmask_b32_e32 v3, v3, v6, vcc
	v_sub_u32_e32 v6, v5, v2
	v_cndmask_b32_e32 v5, v5, v6, vcc
	v_cmp_ge_u32_e32 vcc, v5, v2
	v_add_u32_e32 v5, 1, v3
	v_add_u32_e32 v6, 1, v4
	v_cndmask_b32_e32 v3, v3, v5, vcc
	v_mad_u64_u32 v[4:5], s[8:9], v2, v3, v[2:3]
	v_cmp_ne_u32_e32 vcc, v6, v4
	s_and_saveexec_b64 s[8:9], vcc
	s_xor_b64 s[8:9], exec, s[8:9]
	s_cbranch_execz .LBB0_1063
	v_sub_u32_e32 v0, v4, v2
	v_add_u32_e32 v0, 1, v0
	v_cmp_eq_u32_e32 vcc, v6, v0
	s_cbranch_vccz .Lno_early_wb_8
	buffer_wbl2 sc1
.Lno_early_wb_8:
	v_mov_b32_e32 v0, s64
	v_add_co_u32_e32 v4, vcc, 0x3000, v0
	v_mov_b32_e32 v0, s65
	s_nop 0
	v_addc_co_u32_e32 v5, vcc, 0, v0, vcc
	flat_load_dword v0, v[4:5] offset:1280 sc1
	s_add_u32 s12, s64, 0x3500
	s_addc_u32 s13, s65, 0
	s_waitcnt vmcnt(0) lgkmcnt(0)
	v_cmp_eq_u32_e32 vcc, v0, v3
	s_and_saveexec_b64 s[10:11], vcc
	s_cbranch_execz .LBB0_1062
	s_mov_b32 s1, 1
	s_mov_b64 s[14:15], 0
	s_branch .LBB0_1054

; __device__ __forceinline__ unsigned xb_ld(unsigned* p)              { return __hip_atomic_load(p, __ATOMIC_RELAXED, __HIP_MEMORY_SCOPE_AGENT); }
; __device__ __forceinline__ unsigned xb_add(unsigned* p, unsigned v) { return __hip_atomic_fetch_add(p, v, __ATOMIC_RELAXED, __HIP_MEMORY_SCOPE_AGENT); }
; #define XB_SPIN(cond, bar) do { unsigned _sp = 0; while (cond) { __builtin_amdgcn_s_sleep(1); \
;     if ((++_sp & 255u) == 0u) { if (xb_ld(&(bar)[XB_TMO])) break; if (_sp > XB_SPIN_CAP) { atomicAdd(&(bar)[XB_TMO], 1u); break; } } } } while (0)
; __device__ __forceinline__ void xcd_barrier(const XcdBarrier& b) {
;     ...
;         const unsigned old = xb_add(&bar[XB_XSUB(bx)], 1u);
;         const unsigned gen = old / nloc;
;         if (old + 1u == (gen + 1u) * nloc) {
;             __builtin_amdgcn_fence(__ATOMIC_RELEASE, "agent");
;             asm volatile("s_waitcnt vmcnt(0)" ::: "memory");
;             const unsigned og = xb_add(&bar[XB_TOP], 1u);
;             const unsigned tg = og / nx;
;             if (og + 1u == (tg + 1u) * nx) xb_add(&bar[XB_TOPGEN], 1u);
;             else XB_SPIN(xb_ld(&bar[XB_TOPGEN]) == tg, bar);
;             __builtin_amdgcn_fence(__ATOMIC_ACQUIRE, "agent");
;             asm volatile("s_waitcnt vmcnt(0)" ::: "memory");
;         } else {
;             XB_SPIN(xb_ld(&bar[XB_TOPGEN]) == gen, bar);
.LBB0_1262:
	s_lshl_b32 s0, s0, 6
	s_add_i32 s92, s0, 0x500
	s_lshl_b64 s[0:1], s[92:93], 2
	s_add_u32 s0, s52, s0
	s_addc_u32 s1, s53, s1
	v_mov_b64_e32 v[4:5], s[0:1]
	v_mov_b32_e32 v3, 1
	flat_atomic_add v4, v[4:5], v3 sc0
	v_cvt_f32_u32_e32 v3, v2
	v_sub_u32_e32 v5, 0, v2
	v_rcp_iflag_f32_e32 v3, v3
	s_nop 0
	v_mul_f32_e32 v3, 0x4f7ffffe, v3
	v_cvt_u32_f32_e32 v3, v3
	v_mul_lo_u32 v5, v5, v3
	v_mul_hi_u32 v5, v3, v5
	v_add_u32_e32 v3, v3, v5
	s_waitcnt vmcnt(0) lgkmcnt(0)
	v_mul_hi_u32 v3, v4, v3
	v_mul_lo_u32 v5, v3, v2
	v_sub_u32_e32 v5, v4, v5
	v_cmp_ge_u32_e32 vcc, v5, v2
	v_add_u32_e32 v6, 1, v3
	s_nop 0
	v_cndmask_b32_e32 v3, v3, v6, vcc
	v_sub_u32_e32 v6, v5, v2
	v_cndmask_b32_e32 v5, v5, v6, vcc
	v_cmp_ge_u32_e32 vcc, v5, v2
	v_add_u32_e32 v5, 1, v3
	v_add_u32_e32 v6, 1, v4
	v_cndmask_b32_e32 v3, v3, v5, vcc
	v_mad_u64_u32 v[4:5], s[0:1], v2, v3, v[2:3]
	v_cmp_ne_u32_e32 vcc, v6, v4
	s_and_saveexec_b64 s[0:1], vcc
	s_xor_b64 s[6:7], exec, s[0:1]
	s_cbranch_execz .LBB0_1275
	v_sub_u32_e32 v0, v4, v2
	v_add_u32_e32 v0, 1, v0
	v_cmp_eq_u32_e32 vcc, v6, v0
	s_cbranch_vccz .Lno_early_wb_11
	buffer_wbl2 sc1
.Lno_early_wb_11:
	v_mov_b32_e32 v0, s52
	v_add_co_u32_e32 v4, vcc, 0x3000, v0
	v_mov_b32_e32 v0, s53
	s_nop 0
	v_addc_co_u32_e32 v5, vcc, 0, v0, vcc
	flat_load_dword v0, v[4:5] offset:1280 sc1
	s_add_u32 s10, s52, 0x3500
	s_addc_u32 s11, s53, 0
	s_waitcnt vmcnt(0) lgkmcnt(0)
	v_cmp_eq_u32_e32 vcc, v0, v3
	s_and_saveexec_b64 s[8:9], vcc
	s_cbranch_execz .LBB0_1274
	s_mov_b32 s0, 1
	s_mov_b64 s[12:13], 0
	s_branch .LBB0_1266
